# attention work queues: one agent-scope snapshot of the 8 counters replaces the failing atomicAdd probes of exhausted queues
# speedup vs baseline: 1.0139x; 1.0139x over previous
.LBB0_96:
	s_add_i32 s91, s91, 1
	s_cmp_eq_u32 s91, 8
	s_cbranch_scc1 .LBB0_245
	s_mov_b32 s40, s89
	s_mov_b32 s41, s90
	v_lshlrev_b32_e32 v1, 2, v220
	v_cmp_gt_u32_e32 vcc, 8, v220
	s_and_saveexec_b64 s[2:3], vcc
	s_cbranch_execz .Lqs_nold
	global_load_dword v0, v1, s[40:41] sc1
	s_waitcnt vmcnt(0)
	ds_write_b32 v1, v0 offset:64
.Lqs_nold:
	s_or_b64 exec, exec, s[2:3]
	s_waitcnt lgkmcnt(0)
	s_barrier
	v_and_b32_e32 v1, 7, v223
	v_lshlrev_b32_e32 v1, 2, v1
	ds_read_b32 v0, v1 offset:64
	s_waitcnt lgkmcnt(0)
	s_barrier
.Lqs_scan:
	s_add_i32 s2, s91, s53
	s_and_b32 s2, s2, 7
	s_nop 3
	v_readlane_b32 s3, v0, s2
	s_cmp_ge_u32 s3, s88
	s_cbranch_scc0 .LBB0_97
	s_add_i32 s91, s91, 1
	s_cmp_eq_u32 s91, 8
	s_cbranch_scc0 .Lqs_scan
	s_branch .LBB0_245
